# speedup vs baseline: 1.0064x; 1.0064x over previous
; __device__ __forceinline__ void op_final(const Ctx cx, const Params& p) {
;     const int tid = cx.tid, lane = tid & 63, wave = tid >> 6;
;     const int gw = cx.bid * 8 + wave, NGW = cx.G * 8;
;     for (int m = gw; m < M_TOK; m += NGW) {
;         f32x4* xr = (f32x4*)(p.out + (size_t)m * DM);
;         f32x4 v[8]; float s = 0.f;
; #pragma unroll
;         for (int q = 0; q < 8; ++q) { v[q] = xr[lane + 64 * q]; s += (v[q].x * v[q].x + v[q].y * v[q].y) + (v[q].z * v[q].z + v[q].w * v[q].w); }
;         const float rinv = 1.0f / sqrtf(wave_sum(s) * (1.0f / DM) + EPS);
; #pragma unroll
;         for (int q = 0; q < 8; ++q) { const f32x4 g = ((const f32x4*)p.final_norm)[lane + 64 * q]; xr[lane + 64 * q] = v[q] * rinv * g; }
.LBB0_436:
	s_nop 0
	v_readlane_b32 s4, v255, 10
	v_readlane_b32 s5, v255, 11
	s_andn2_b64 vcc, exec, s[4:5]
	v_readlane_b32 s33, v255, 15
	v_readlane_b32 s34, v255, 13
	s_cbranch_vccnz .LBB0_441
	v_ashrrev_i32_e32 v0, 6, v201
	s_lshl_b32 s4, s33, 3
	v_add_u32_e32 v49, s4, v0
	s_movk_i32 s0, 0x4000
	v_cmp_gt_i32_e32 vcc, s0, v49
	s_and_saveexec_b64 s[2:3], vcc
	s_cbranch_execz .LBB0_440
	v_and_b32_e32 v1, 64, v190
	v_add_u32_e32 v1, 64, v1
	v_xor_b32_e32 v2, 1, v190
	v_cmp_lt_i32_e32 vcc, v2, v1
	v_readlane_b32 s12, v254, 52
	v_readlane_b32 s13, v254, 53
	v_cndmask_b32_e32 v2, v190, v2, vcc
	v_lshlrev_b32_e32 v50, 2, v2
	v_xor_b32_e32 v2, 2, v190
	v_cmp_lt_i32_e32 vcc, v2, v1
	v_mov_b32_e32 v3, v181
	s_ashr_i32 s5, s4, 31
	v_cndmask_b32_e32 v2, v190, v2, vcc
	v_lshlrev_b32_e32 v51, 2, v2
	v_xor_b32_e32 v2, 4, v190
	v_cmp_lt_i32_e32 vcc, v2, v1
	s_lshl_b32 s8, s34, 3
	s_ashr_i32 s9, s8, 31
	v_cndmask_b32_e32 v2, v190, v2, vcc
	v_lshlrev_b32_e32 v52, 2, v2
	v_xor_b32_e32 v2, 8, v190
	v_cmp_lt_i32_e32 vcc, v2, v1
	s_lshl_b64 s[10:11], s[8:9], 13
	v_readlane_b32 s14, v254, 54
	v_cndmask_b32_e32 v2, v190, v2, vcc
	v_lshlrev_b32_e32 v53, 2, v2
	v_xor_b32_e32 v2, 16, v190
	v_cmp_lt_i32_e32 vcc, v2, v1
	v_readlane_b32 s15, v254, 55
	s_nop 0
	v_cndmask_b32_e32 v2, v190, v2, vcc
	v_lshlrev_b32_e32 v54, 2, v2
	v_xor_b32_e32 v2, 32, v190
	v_cmp_lt_i32_e32 vcc, v2, v1
	s_nop 1
	v_cndmask_b32_e32 v1, v190, v2, vcc
	v_lshlrev_b32_e32 v55, 2, v1
	v_lshlrev_b32_e32 v1, 4, v201
	v_and_b32_e32 v180, 0x3f0, v1
	v_or_b32_e32 v2, 0x1000, v180
	v_ashrrev_i32_e32 v1, 31, v0
	s_waitcnt vmcnt(0)
	v_lshl_add_u64 v[38:39], s[12:13], 0, v[2:3]
	v_or_b32_e32 v2, 0x1400, v180
	v_lshl_add_u64 v[0:1], v[0:1], 0, s[4:5]
	v_lshl_add_u64 v[40:41], s[12:13], 0, v[2:3]
	v_or_b32_e32 v2, 0x1800, v180
	v_lshlrev_b64 v[0:1], 13, v[0:1]
	v_readlane_b32 s4, v254, 56
	v_lshl_add_u64 v[42:43], s[12:13], 0, v[2:3]
	v_or_b32_e32 v2, 0x1c00, v180
	v_or_b32_e32 v0, v0, v180
	v_readlane_b32 s5, v254, 57
	v_lshl_add_u64 v[36:37], s[12:13], 0, v[180:181]
	s_waitcnt lgkmcnt(0)
	v_lshl_add_u64 v[44:45], s[12:13], 0, v[2:3]
	v_lshl_add_u64 v[46:47], s[4:5], 0, v[0:1]
	s_mov_b64 s[12:13], 0
	global_load_dwordx4 v[56:59], v[36:37], off
	global_load_dwordx4 v[60:63], v[36:37], off offset:1024
	global_load_dwordx4 v[64:67], v[36:37], off offset:2048
	global_load_dwordx4 v[68:71], v[36:37], off offset:3072
	global_load_dwordx4 v[72:75], v[38:39], off
	global_load_dwordx4 v[76:79], v[40:41], off
	global_load_dwordx4 v[80:83], v[42:43], off
	global_load_dwordx4 v[84:87], v[44:45], off
	global_load_dwordx4 v[88:91], v[46:47], off offset:-4096
	global_load_dwordx4 v[92:95], v[46:47], off offset:-3072
	global_load_dwordx4 v[96:99], v[46:47], off offset:-2048
	global_load_dwordx4 v[100:103], v[46:47], off offset:-1024
	global_load_dwordx4 v[104:107], v[46:47], off
	global_load_dwordx4 v[108:111], v[46:47], off offset:1024
	global_load_dwordx4 v[112:115], v[46:47], off offset:2048
	global_load_dwordx4 v[116:119], v[46:47], off offset:3072
	s_waitcnt vmcnt(0)
.LBB0_439:
	s_waitcnt vmcnt(8)
	v_mov_b64_e32 v[0:1], v[88:89]
	v_mov_b64_e32 v[2:3], v[90:91]
	v_mov_b64_e32 v[4:5], v[92:93]
	v_mov_b64_e32 v[6:7], v[94:95]
	v_mov_b64_e32 v[8:9], v[96:97]
	v_mov_b64_e32 v[10:11], v[98:99]
	v_mov_b64_e32 v[12:13], v[100:101]
	v_mov_b64_e32 v[14:15], v[102:103]
	v_mov_b64_e32 v[16:17], v[104:105]
	v_mov_b64_e32 v[18:19], v[106:107]
	v_mov_b64_e32 v[20:21], v[108:109]
	v_mov_b64_e32 v[22:23], v[110:111]
	v_mov_b64_e32 v[24:25], v[112:113]
	v_mov_b64_e32 v[26:27], v[114:115]
	v_mov_b64_e32 v[28:29], v[116:117]
	v_mov_b64_e32 v[30:31], v[118:119]
	v_lshl_add_u64 v[120:121], v[46:47], 0, s[10:11]
	v_readfirstlane_b32 s4, v49
	s_nop 3
	s_add_i32 s4, s4, s8
	s_cmp_gt_i32 s4, s65
	s_cbranch_scc1 .Lfin_noload
	global_load_dwordx4 v[88:91], v[120:121], off offset:-4096
	global_load_dwordx4 v[92:95], v[120:121], off offset:-3072
	global_load_dwordx4 v[96:99], v[120:121], off offset:-2048
	global_load_dwordx4 v[100:103], v[120:121], off offset:-1024
	global_load_dwordx4 v[104:107], v[120:121], off
	global_load_dwordx4 v[108:111], v[120:121], off offset:1024
	global_load_dwordx4 v[112:115], v[120:121], off offset:2048
	global_load_dwordx4 v[116:119], v[120:121], off offset:3072
; __device__ __forceinline__ void op_final(const Ctx cx, const Params& p) {
;     ...
;         f32x4 v[8]; float s = 0.f;
; #pragma unroll
;         for (int q = 0; q < 8; ++q) { v[q] = xr[lane + 64 * q]; s += (v[q].x * v[q].x + v[q].y * v[q].y) + (v[q].z * v[q].z + v[q].w * v[q].w); }
;         const float rinv = 1.0f / sqrtf(wave_sum(s) * (1.0f / DM) + EPS);
; #pragma unroll
;         for (int q = 0; q < 8; ++q) { const f32x4 g = ((const f32x4*)p.final_norm)[lane + 64 * q]; xr[lane + 64 * q] = v[q] * rinv * g; }
;     }
.Lfin_noload:
	v_mul_f32_e32 v32, v0, v0
	v_mul_f32_e32 v33, v8, v8
	v_mul_f32_e32 v34, v16, v16
	v_mul_f32_e32 v35, v24, v24
	v_fmac_f32_e32 v32, v1, v1
	v_fmac_f32_e32 v33, v9, v9
	v_fmac_f32_e32 v34, v17, v17
	v_fmac_f32_e32 v35, v25, v25
	v_fmac_f32_e32 v32, v2, v2
	v_fmac_f32_e32 v33, v10, v10
	v_fmac_f32_e32 v34, v18, v18
	v_fmac_f32_e32 v35, v26, v26
	v_fmac_f32_e32 v32, v3, v3
	v_fmac_f32_e32 v33, v11, v11
	v_fmac_f32_e32 v34, v19, v19
	v_fmac_f32_e32 v35, v27, v27
	v_fmac_f32_e32 v32, v4, v4
	v_fmac_f32_e32 v33, v12, v12
	v_fmac_f32_e32 v34, v20, v20
	v_fmac_f32_e32 v35, v28, v28
	v_fmac_f32_e32 v32, v5, v5
	v_fmac_f32_e32 v33, v13, v13
	v_fmac_f32_e32 v34, v21, v21
	v_fmac_f32_e32 v35, v29, v29
	v_fmac_f32_e32 v32, v6, v6
	v_fmac_f32_e32 v33, v14, v14
	v_fmac_f32_e32 v34, v22, v22
	v_fmac_f32_e32 v35, v30, v30
	v_fmac_f32_e32 v32, v7, v7
	v_fmac_f32_e32 v33, v15, v15
	v_fmac_f32_e32 v34, v23, v23
	v_fmac_f32_e32 v35, v31, v31
	v_add_f32_e32 v32, v32, v33
	v_add_f32_e32 v34, v34, v35
	v_add_f32_e32 v32, v32, v34
	ds_bpermute_b32 v33, v50, v32
	s_waitcnt lgkmcnt(0)
	v_add_f32_e32 v32, v32, v33
	ds_bpermute_b32 v33, v51, v32
	s_waitcnt lgkmcnt(0)
	v_add_f32_e32 v32, v32, v33
	ds_bpermute_b32 v33, v52, v32
	s_waitcnt lgkmcnt(0)
	v_add_f32_e32 v32, v32, v33
	ds_bpermute_b32 v33, v53, v32
	s_waitcnt lgkmcnt(0)
	v_add_f32_e32 v32, v32, v33
	ds_bpermute_b32 v33, v54, v32
	s_waitcnt lgkmcnt(0)
	v_add_f32_e32 v32, v32, v33
	ds_bpermute_b32 v33, v55, v32
	s_waitcnt lgkmcnt(0)
	v_add_f32_e32 v32, v32, v33
	v_fmamk_f32 v32, v32, 0x3a000000, v186
	v_cmp_gt_f32_e32 vcc, s79, v32
	v_mul_f32_e32 v33, 0x4f800000, v32
	s_nop 0
	v_cndmask_b32_e32 v32, v32, v33, vcc
	v_sqrt_f32_e32 v33, v32
	s_nop 0
	v_add_u32_e32 v34, -1, v33
	v_fma_f32 v35, -v34, v33, v32
	v_cmp_ge_f32_e64 s[6:7], 0, v35
	v_add_u32_e32 v35, 1, v33
	s_nop 0
	v_cndmask_b32_e64 v34, v33, v34, s[6:7]
	v_fma_f32 v33, -v35, v33, v32
	v_cmp_lt_f32_e64 s[6:7], 0, v33
	s_nop 1
	v_cndmask_b32_e64 v33, v34, v35, s[6:7]
	v_mul_f32_e32 v34, 0x37800000, v33
	v_cndmask_b32_e32 v33, v33, v34, vcc
	v_cmp_class_f32_e32 vcc, v32, v187
	s_nop 1
	v_cndmask_b32_e32 v32, v33, v32, vcc
	v_div_scale_f32 v33, s[4:5], v32, v32, 1.0
	v_rcp_f32_e32 v34, v33
	s_nop 0
	v_fma_f32 v35, -v33, v34, 1.0
	v_fmac_f32_e32 v34, v35, v34
	v_div_scale_f32 v35, vcc, 1.0, v32, 1.0
	v_mul_f32_e32 v48, v35, v34
	v_fma_f32 v123, -v33, v48, v35
	v_fmac_f32_e32 v48, v123, v34
	v_fma_f32 v33, -v33, v48, v35
	v_div_fmas_f32 v33, v33, v34, v48
	v_div_fixup_f32 v48, v33, v32, 1.0
	v_pk_mul_f32 v[0:1], v[0:1], v[48:49] op_sel_hi:[1,0]
	v_pk_mul_f32 v[2:3], v[2:3], v[48:49] op_sel_hi:[1,0]
	v_pk_mul_f32 v[4:5], v[4:5], v[48:49] op_sel_hi:[1,0]
	v_pk_mul_f32 v[6:7], v[6:7], v[48:49] op_sel_hi:[1,0]
	v_pk_mul_f32 v[8:9], v[8:9], v[48:49] op_sel_hi:[1,0]
	v_pk_mul_f32 v[10:11], v[10:11], v[48:49] op_sel_hi:[1,0]
	v_pk_mul_f32 v[12:13], v[12:13], v[48:49] op_sel_hi:[1,0]
	v_pk_mul_f32 v[14:15], v[14:15], v[48:49] op_sel_hi:[1,0]
	v_pk_mul_f32 v[16:17], v[16:17], v[48:49] op_sel_hi:[1,0]
	v_pk_mul_f32 v[18:19], v[18:19], v[48:49] op_sel_hi:[1,0]
	v_pk_mul_f32 v[20:21], v[20:21], v[48:49] op_sel_hi:[1,0]
	v_pk_mul_f32 v[22:23], v[22:23], v[48:49] op_sel_hi:[1,0]
	v_pk_mul_f32 v[24:25], v[24:25], v[48:49] op_sel_hi:[1,0]
	v_pk_mul_f32 v[26:27], v[26:27], v[48:49] op_sel_hi:[1,0]
	v_pk_mul_f32 v[28:29], v[28:29], v[48:49] op_sel_hi:[1,0]
	v_pk_mul_f32 v[30:31], v[30:31], v[48:49] op_sel_hi:[1,0]
	v_pk_mul_f32 v[0:1], v[56:57], v[0:1]
	v_pk_mul_f32 v[2:3], v[58:59], v[2:3]
	v_pk_mul_f32 v[4:5], v[60:61], v[4:5]
	v_pk_mul_f32 v[6:7], v[62:63], v[6:7]
	v_pk_mul_f32 v[8:9], v[64:65], v[8:9]
	v_pk_mul_f32 v[10:11], v[66:67], v[10:11]
	v_pk_mul_f32 v[12:13], v[68:69], v[12:13]
	v_pk_mul_f32 v[14:15], v[70:71], v[14:15]
	v_pk_mul_f32 v[16:17], v[72:73], v[16:17]
	v_pk_mul_f32 v[18:19], v[74:75], v[18:19]
	v_pk_mul_f32 v[20:21], v[76:77], v[20:21]
	v_pk_mul_f32 v[22:23], v[78:79], v[22:23]
	v_pk_mul_f32 v[24:25], v[80:81], v[24:25]
	v_pk_mul_f32 v[26:27], v[82:83], v[26:27]
	v_pk_mul_f32 v[28:29], v[84:85], v[28:29]
	v_pk_mul_f32 v[30:31], v[86:87], v[30:31]
	global_store_dwordx4 v[46:47], v[0:3], off offset:-4096
	global_store_dwordx4 v[46:47], v[4:7], off offset:-3072
	global_store_dwordx4 v[46:47], v[8:11], off offset:-2048
	global_store_dwordx4 v[46:47], v[12:15], off offset:-1024
	global_store_dwordx4 v[46:47], v[16:19], off
	global_store_dwordx4 v[46:47], v[20:23], off offset:1024
	global_store_dwordx4 v[46:47], v[24:27], off offset:2048
	global_store_dwordx4 v[46:47], v[28:31], off offset:3072
	v_add_u32_e32 v49, s8, v49
	v_cmp_lt_i32_e32 vcc, s65, v49
	s_or_b64 s[12:13], vcc, s[12:13]
	v_mov_b64_e32 v[46:47], v[120:121]
	s_andn2_b64 exec, exec, s[12:13]
	s_cbranch_execnz .LBB0_439
